# f9 + gate-GEMM sigmoid epilogue re-derived to 5 VALU per element (folded scales, clamped fma + rcp, cvt_pk_u8 packing)
# speedup vs baseline: 1.0054x; 1.0007x over previous
; __device__ __forceinline__ float logsigmoidf_(float x) { return fminf(x, 0.f) - flog(1.0f + fexp(-fabsf(x))); }
;     __device__ __forceinline__ void operator()(const Acc& acc, const Unit& u, int wr, int wc, int fr, int fq) const {
;         const int row0 = u.pm * BM + wr * 64 + fr; const int colt = u.pn * BM + wc * 32 + 8 * fq;
;         if (u.pn >= 24) {
;             const int zc = ((u.pn < 28) ? 6144 + (u.pn - 24) * BM : (u.pn < 30) ? 7168 + (u.pn - 28) * BM : 2560 + (u.pn - 30) * BM) + wc * 32 + 8 * fq;
;             const bool isa = (u.pn >= 28 && u.pn < 30);
;             f32x4 bb[2][2];
; #pragma unroll
;             for (int bj = 0; bj < 2; ++bj)
; #pragma unroll
;                 for (int n = 0; n < 2; ++n) bb[bj][n] = isa ? *(const f32x4*)(b_alpha + (zc - 7168) + bj * HALF + 4 * n) : (f32x4){0.f, 0.f, 0.f, 0.f};
;             float rz[2][4];
; #pragma unroll
;             for (int ai = 0; ai < 2; ++ai)
; #pragma unroll
;                 for (int m = 0; m < 4; ++m) rz[ai][m] = rinvx[row0 + ai * HALF + m * 16] * (1.0f / 512.0f);
; #pragma unroll
;             for (int ai = 0; ai < 2; ++ai)
; #pragma unroll
;                 for (int m = 0; m < 4; ++m) { const int row = row0 + ai * HALF + m * 16; const float rs = rz[ai][m]; bf16* rowp = Z + (size_t)row * NZ + zc;
; #pragma unroll
;                     for (int bj = 0; bj < 2; ++bj) { f32x4 v0 = acc[ai][bj][m][0] * rs + bb[bj][0], v1 = acc[ai][bj][m][1] * rs + bb[bj][1];
;                         if (isa) {
; #pragma unroll
;                             for (int e = 0; e < 4; ++e) { v0[e] = logsigmoidf_(v0[e]) * 0.0625f; v1[e] = logsigmoidf_(v1[e]) * 0.0625f; } }
;                         u32x4 w; w.x = pk2(v0[0], v0[1]); w.y = pk2(v0[2], v0[3]); w.z = pk2(v1[0], v1[1]); w.w = pk2(v1[2], v1[3]);
;                         *(u32x4*)(rowp + bj * HALF) = w; } }
;             return;
;         }
;         f32x4 bv[2][2];
; #pragma unroll
;         for (int bj = 0; bj < 2; ++bj)
; #pragma unroll
;             for (int n = 0; n < 2; ++n) bv[bj][n] = *(const f32x4*)(b_gate + colt + bj * HALF + 4 * n);
;         float rsv[2][4];
; #pragma unroll
;         for (int ai = 0; ai < 2; ++ai)
; #pragma unroll
;             for (int m = 0; m < 4; ++m) rsv[ai][m] = rinvx[row0 + ai * HALF + m * 16] * (1.0f / 512.0f);
; #pragma unroll
;         for (int ai = 0; ai < 2; ++ai)
; #pragma unroll
.LBB0_570:
	s_nop 15
	s_nop 7
	v_lshl_add_u32 v24, s42, 8, v193
	s_lshl_b32 s1, s0, 8
	v_or_b32_e32 v22, 16, v24
	v_or_b32_e32 v20, 32, v24
	v_or_b32_e32 v18, 48, v24
	s_mov_b64 s[42:43], -1
	s_cmp_lt_i32 s0, 24
	v_ashrrev_i32_e32 v25, 31, v24
	v_add_u32_e32 v183, 0x80, v24
	v_add_u32_e32 v182, 0x90, v24
	v_add_u32_e32 v181, 0xa0, v24
	v_add_u32_e32 v180, 0xb0, v24
	v_ashrrev_i32_e32 v23, 31, v22
	v_ashrrev_i32_e32 v21, 31, v20
	v_ashrrev_i32_e32 v19, 31, v18
	s_cbranch_scc0 .LBB0_573
	v_or_b32_e32 v26, s1, v189
	v_ashrrev_i32_e32 v27, 31, v26
	v_lshl_add_u64 v[2:3], v[26:27], 2, s[44:45]
	v_lshl_add_u64 v[4:5], v[24:25], 2, s[20:21]
	v_lshl_add_u64 v[6:7], v[22:23], 2, s[20:21]
	v_lshl_add_u64 v[8:9], v[20:21], 2, s[20:21]
	v_lshl_add_u64 v[10:11], v[18:19], 2, s[20:21]
	global_load_dword v32, v[4:5], off
	global_load_dword v33, v[6:7], off
	global_load_dword v170, v[8:9], off
	global_load_dword v185, v[10:11], off
	global_load_dword v195, v[4:5], off offset:512
	global_load_dword v196, v[4:5], off offset:576
	global_load_dword v197, v[4:5], off offset:640
	global_load_dword v198, v[4:5], off offset:704
	global_load_dwordx4 v[14:17], v[2:3], off
	global_load_dwordx4 v[10:13], v[2:3], off offset:16
	global_load_dwordx4 v[6:9], v[2:3], off offset:512
	s_nop 0
	global_load_dwordx4 v[2:5], v[2:3], off offset:528
	v_mov_b64_e32 v[28:29], s[88:89]
	v_mad_i64_i32 v[30:31], s[42:43], v24, s62, v[28:29]
	v_lshl_add_u64 v[186:187], v[30:31], 0, v[26:27]
	s_waitcnt vmcnt(0)
	s_mov_b32 s98, 0x3b808081
	v_mul_f32_e32 v2, 0xbfb8aa3b, v2
	v_mul_f32_e32 v3, 0xbfb8aa3b, v3
	v_mul_f32_e32 v4, 0xbfb8aa3b, v4
	v_mul_f32_e32 v5, 0xbfb8aa3b, v5
	v_mul_f32_e32 v6, 0xbfb8aa3b, v6
	v_mul_f32_e32 v7, 0xbfb8aa3b, v7
	v_mul_f32_e32 v8, 0xbfb8aa3b, v8
	v_mul_f32_e32 v9, 0xbfb8aa3b, v9
	v_mul_f32_e32 v10, 0xbfb8aa3b, v10
	v_mul_f32_e32 v11, 0xbfb8aa3b, v11
	v_mul_f32_e32 v12, 0xbfb8aa3b, v12
	v_mul_f32_e32 v13, 0xbfb8aa3b, v13
	v_mul_f32_e32 v14, 0xbfb8aa3b, v14
	v_mul_f32_e32 v15, 0xbfb8aa3b, v15
	v_mul_f32_e32 v16, 0xbfb8aa3b, v16
	v_mul_f32_e32 v17, 0xbfb8aa3b, v17
	v_mul_f32_e32 v199, 0xbb38aa3b, v32
	v_mul_f32_e32 v200, 0xbb38aa3b, v33
	v_mul_f32_e32 v184, 0xbb38aa3b, v170
	v_mul_f32_e32 v170, 0xbb38aa3b, v185
	v_mul_f32_e32 v33, 0xbb38aa3b, v195
	v_mul_f32_e32 v32, 0xbb38aa3b, v196
	v_mul_f32_e32 v31, 0xbb38aa3b, v197
	v_mul_f32_e32 v30, 0xbb38aa3b, v198
	v_fma_f32 v230, v158, v199, v14
	v_fma_f32 v231, v154, v199, v10
	v_fma_f32 v232, v159, v199, v15
	v_fma_f32 v233, v155, v199, v11
	v_fma_f32 v234, v160, v199, v16
	v_fma_f32 v235, v156, v199, v12
	v_fma_f32 v236, v161, v199, v17
	v_fma_f32 v237, v157, v199, v13
	v_exp_f32_e32 v230, v230
	v_exp_f32_e32 v231, v231
	v_exp_f32_e32 v232, v232
	v_exp_f32_e32 v233, v233
	v_exp_f32_e32 v234, v234
	v_exp_f32_e32 v235, v235
	v_exp_f32_e32 v236, v236
	v_exp_f32_e32 v237, v237
	s_nop 0
	v_fma_f32 v230, v230, s98, s98 clamp
	v_fma_f32 v231, v231, s98, s98 clamp
	v_fma_f32 v232, v232, s98, s98 clamp
	v_fma_f32 v233, v233, s98, s98 clamp
	v_fma_f32 v234, v234, s98, s98 clamp
	v_fma_f32 v235, v235, s98, s98 clamp
	v_fma_f32 v236, v236, s98, s98 clamp
	v_fma_f32 v237, v237, s98, s98 clamp
	v_rcp_f32_e32 v230, v230
	v_rcp_f32_e32 v231, v231
	v_rcp_f32_e32 v232, v232
	v_rcp_f32_e32 v233, v233
	v_rcp_f32_e32 v234, v234
	v_rcp_f32_e32 v235, v235
	v_rcp_f32_e32 v236, v236
	v_rcp_f32_e32 v237, v237
	s_nop 0
	v_cvt_pk_u8_f32 v238, v230, 0, 0
	v_cvt_pk_u8_f32 v238, v232, 1, v238
	v_cvt_pk_u8_f32 v238, v234, 2, v238
	v_cvt_pk_u8_f32 v238, v236, 3, v238
	v_cvt_pk_u8_f32 v239, v231, 0, 0
	v_cvt_pk_u8_f32 v239, v233, 1, v239
	v_cvt_pk_u8_f32 v239, v235, 2, v239
	v_cvt_pk_u8_f32 v239, v237, 3, v239
	global_store_dwordx2 v[186:187], v[238:239], off
	v_fma_f32 v230, v150, v199, v6
	v_fma_f32 v231, v146, v199, v2
	v_fma_f32 v232, v151, v199, v7
	v_fma_f32 v233, v147, v199, v3
	v_fma_f32 v234, v152, v199, v8
	v_fma_f32 v235, v148, v199, v4
	v_fma_f32 v236, v153, v199, v9
	v_fma_f32 v237, v149, v199, v5
	v_exp_f32_e32 v230, v230
	v_exp_f32_e32 v231, v231
	v_exp_f32_e32 v232, v232
	v_exp_f32_e32 v233, v233
	v_exp_f32_e32 v234, v234
	v_exp_f32_e32 v235, v235
	v_exp_f32_e32 v236, v236
	v_exp_f32_e32 v237, v237
	s_nop 0
	v_fma_f32 v230, v230, s98, s98 clamp
	v_fma_f32 v231, v231, s98, s98 clamp
	v_fma_f32 v232, v232, s98, s98 clamp
	v_fma_f32 v233, v233, s98, s98 clamp
	v_fma_f32 v234, v234, s98, s98 clamp
	v_fma_f32 v235, v235, s98, s98 clamp
	v_fma_f32 v236, v236, s98, s98 clamp
	v_fma_f32 v237, v237, s98, s98 clamp
	v_rcp_f32_e32 v230, v230
	v_rcp_f32_e32 v231, v231
	v_rcp_f32_e32 v232, v232
	v_rcp_f32_e32 v233, v233
	v_rcp_f32_e32 v234, v234
	v_rcp_f32_e32 v235, v235
	v_rcp_f32_e32 v236, v236
	v_rcp_f32_e32 v237, v237
	s_nop 0
	v_cvt_pk_u8_f32 v240, v230, 0, 0
	v_cvt_pk_u8_f32 v240, v232, 1, v240
	v_cvt_pk_u8_f32 v240, v234, 2, v240
	v_cvt_pk_u8_f32 v240, v236, 3, v240
	v_cvt_pk_u8_f32 v241, v231, 0, 0
	v_cvt_pk_u8_f32 v241, v233, 1, v241
	v_cvt_pk_u8_f32 v241, v235, 2, v241
	v_cvt_pk_u8_f32 v241, v237, 3, v241
	global_store_dwordx2 v[186:187], v[240:241], off offset:128
	v_fma_f32 v230, v142, v200, v14
	v_fma_f32 v231, v143, v200, v15
	v_fma_f32 v232, v138, v200, v10
	v_fma_f32 v233, v139, v200, v11
	v_fma_f32 v234, v144, v200, v16
	v_fma_f32 v235, v145, v200, v17
	v_fma_f32 v236, v140, v200, v12
	v_fma_f32 v237, v141, v200, v13
	v_exp_f32_e32 v230, v230
	v_exp_f32_e32 v231, v231
	v_exp_f32_e32 v232, v232
	v_exp_f32_e32 v233, v233
	v_exp_f32_e32 v234, v234
	v_exp_f32_e32 v235, v235
	v_exp_f32_e32 v236, v236
	v_exp_f32_e32 v237, v237
	s_nop 0
	v_fma_f32 v230, v230, s98, s98 clamp
	v_fma_f32 v231, v231, s98, s98 clamp
	v_fma_f32 v232, v232, s98, s98 clamp
; __device__ __forceinline__ float sigmoidf_(float x) { return frcp(1.0f + fexp(-x)); }
;     __device__ __forceinline__ void operator()(const Acc& acc, const Unit& u, int wr, int wc, int fr, int fq) const {
;     ...
;             for (int m = 0; m < 4; ++m) { const int row = row0 + ai * HALF + m * 16; const float rs = rsv[ai][m]; unsigned char* rowp = GT + (size_t)row * NGT + colt;
; #pragma unroll
;                 for (int bj = 0; bj < 2; ++bj) { f32x4 v0 = acc[ai][bj][m][0] * rs + bv[bj][0], v1 = acc[ai][bj][m][1] * rs + bv[bj][1];
;                     unsigned q0[4], q1[4];
; #pragma unroll
;                     for (int e = 0; e < 4; ++e) { q0[e] = (unsigned)fmaxf(sigmoidf_(v0[e]) * 255.0f + 0.5f, 1.0f); q1[e] = (unsigned)fmaxf(sigmoidf_(v1[e]) * 255.0f + 0.5f, 1.0f); }
;                     u32x2 w; w.x = q0[0] | (q0[1] << 8) | (q0[2] << 16) | (q0[3] << 24); w.y = q1[0] | (q1[1] << 8) | (q1[2] << 16) | (q1[3] << 24);
;                     *(u32x2*)(rowp + bj * HALF) = w; } }
	v_fma_f32 v233, v233, s98, s98 clamp
	v_fma_f32 v234, v234, s98, s98 clamp
	v_fma_f32 v235, v235, s98, s98 clamp
	v_fma_f32 v236, v236, s98, s98 clamp
	v_fma_f32 v237, v237, s98, s98 clamp
	v_rcp_f32_e32 v230, v230
	v_rcp_f32_e32 v231, v231
	v_rcp_f32_e32 v232, v232
	v_rcp_f32_e32 v233, v233
	v_rcp_f32_e32 v234, v234
	v_rcp_f32_e32 v235, v235
	v_rcp_f32_e32 v236, v236
	v_rcp_f32_e32 v237, v237
	s_nop 0
	v_cvt_pk_u8_f32 v242, v230, 0, 0
	v_cvt_pk_u8_f32 v242, v231, 1, v242
	v_cvt_pk_u8_f32 v242, v234, 2, v242
	v_cvt_pk_u8_f32 v242, v235, 3, v242
	v_cvt_pk_u8_f32 v243, v232, 0, 0
	v_cvt_pk_u8_f32 v243, v233, 1, v243
	v_cvt_pk_u8_f32 v243, v236, 2, v243
	v_cvt_pk_u8_f32 v243, v237, 3, v243
	v_mad_i64_i32 v[186:187], s[42:43], v22, s62, v[28:29]
	v_lshl_add_u64 v[186:187], v[186:187], 0, v[26:27]
	global_store_dwordx2 v[186:187], v[242:243], off
	v_fma_f32 v230, v134, v200, v6
	v_fma_f32 v231, v135, v200, v7
	v_fma_f32 v232, v130, v200, v2
	v_fma_f32 v233, v131, v200, v3
	v_fma_f32 v234, v136, v200, v8
	v_fma_f32 v235, v137, v200, v9
	v_fma_f32 v236, v132, v200, v4
	v_fma_f32 v237, v133, v200, v5
	v_exp_f32_e32 v230, v230
	v_exp_f32_e32 v231, v231
	v_exp_f32_e32 v232, v232
	v_exp_f32_e32 v233, v233
	v_exp_f32_e32 v234, v234
	v_exp_f32_e32 v235, v235
	v_exp_f32_e32 v236, v236
	v_exp_f32_e32 v237, v237
	s_nop 0
	v_fma_f32 v230, v230, s98, s98 clamp
	v_fma_f32 v231, v231, s98, s98 clamp
	v_fma_f32 v232, v232, s98, s98 clamp
	v_fma_f32 v233, v233, s98, s98 clamp
	v_fma_f32 v234, v234, s98, s98 clamp
	v_fma_f32 v235, v235, s98, s98 clamp
	v_fma_f32 v236, v236, s98, s98 clamp
	v_fma_f32 v237, v237, s98, s98 clamp
	v_rcp_f32_e32 v230, v230
	v_rcp_f32_e32 v231, v231
	v_rcp_f32_e32 v232, v232
	v_rcp_f32_e32 v233, v233
	v_rcp_f32_e32 v234, v234
	v_rcp_f32_e32 v235, v235
	v_rcp_f32_e32 v236, v236
	v_rcp_f32_e32 v237, v237
	s_nop 0
	v_cvt_pk_u8_f32 v244, v230, 0, 0
	v_cvt_pk_u8_f32 v244, v231, 1, v244
	v_cvt_pk_u8_f32 v244, v234, 2, v244
	v_cvt_pk_u8_f32 v244, v235, 3, v244
	v_cvt_pk_u8_f32 v245, v232, 0, 0
	v_cvt_pk_u8_f32 v245, v233, 1, v245
	v_cvt_pk_u8_f32 v245, v236, 2, v245
	v_cvt_pk_u8_f32 v245, v237, 3, v245
	global_store_dwordx2 v[186:187], v[244:245], off offset:128
	v_fma_f32 v230, v126, v184, v14
	v_fma_f32 v231, v127, v184, v15
	v_fma_f32 v232, v122, v184, v10
	v_fma_f32 v233, v123, v184, v11
	v_fma_f32 v234, v128, v184, v16
	v_fma_f32 v235, v129, v184, v17
	v_fma_f32 v236, v124, v184, v12
	v_fma_f32 v237, v125, v184, v13
	v_exp_f32_e32 v230, v230
	v_exp_f32_e32 v231, v231
	v_exp_f32_e32 v232, v232
	v_exp_f32_e32 v233, v233
	v_exp_f32_e32 v234, v234
	v_exp_f32_e32 v235, v235
	v_exp_f32_e32 v236, v236
	v_exp_f32_e32 v237, v237
	s_nop 0
	v_fma_f32 v230, v230, s98, s98 clamp
	v_fma_f32 v231, v231, s98, s98 clamp
	v_fma_f32 v232, v232, s98, s98 clamp
	v_fma_f32 v233, v233, s98, s98 clamp
	v_fma_f32 v234, v234, s98, s98 clamp
	v_fma_f32 v235, v235, s98, s98 clamp
	v_fma_f32 v236, v236, s98, s98 clamp
	v_fma_f32 v237, v237, s98, s98 clamp
	v_rcp_f32_e32 v230, v230
	v_rcp_f32_e32 v231, v231
	v_rcp_f32_e32 v232, v232
	v_rcp_f32_e32 v233, v233
	v_rcp_f32_e32 v234, v234
	v_rcp_f32_e32 v235, v235
	v_rcp_f32_e32 v236, v236
	v_rcp_f32_e32 v237, v237
	s_nop 0
	v_cvt_pk_u8_f32 v238, v230, 0, 0
	v_cvt_pk_u8_f32 v238, v231, 1, v238
	v_cvt_pk_u8_f32 v238, v234, 2, v238
	v_cvt_pk_u8_f32 v238, v235, 3, v238
	v_cvt_pk_u8_f32 v239, v232, 0, 0
	v_cvt_pk_u8_f32 v239, v233, 1, v239
	v_cvt_pk_u8_f32 v239, v236, 2, v239
	v_cvt_pk_u8_f32 v239, v237, 3, v239
	v_mad_i64_i32 v[186:187], s[42:43], v20, s62, v[28:29]
	v_lshl_add_u64 v[186:187], v[186:187], 0, v[26:27]
	global_store_dwordx2 v[186:187], v[238:239], off
	v_fma_f32 v230, v118, v184, v6
	v_fma_f32 v231, v114, v184, v2
	v_fma_f32 v232, v119, v184, v7
	v_fma_f32 v233, v115, v184, v3
	v_fma_f32 v234, v120, v184, v8
	v_fma_f32 v235, v116, v184, v4
	v_fma_f32 v236, v121, v184, v9
	v_fma_f32 v237, v117, v184, v5
	v_exp_f32_e32 v230, v230
	v_exp_f32_e32 v231, v231
	v_exp_f32_e32 v232, v232
	v_exp_f32_e32 v233, v233
	v_exp_f32_e32 v234, v234
	v_exp_f32_e32 v235, v235
	v_exp_f32_e32 v236, v236
	v_exp_f32_e32 v237, v237
	s_nop 0
	v_fma_f32 v230, v230, s98, s98 clamp
	v_fma_f32 v231, v231, s98, s98 clamp
	v_fma_f32 v232, v232, s98, s98 clamp
	v_fma_f32 v233, v233, s98, s98 clamp
	v_fma_f32 v234, v234, s98, s98 clamp
	v_fma_f32 v235, v235, s98, s98 clamp
	v_fma_f32 v236, v236, s98, s98 clamp
	v_fma_f32 v237, v237, s98, s98 clamp
	v_rcp_f32_e32 v230, v230
	v_rcp_f32_e32 v231, v231
	v_rcp_f32_e32 v232, v232
	v_rcp_f32_e32 v233, v233
	v_rcp_f32_e32 v234, v234
	v_rcp_f32_e32 v235, v235
	v_rcp_f32_e32 v236, v236
	v_rcp_f32_e32 v237, v237
	s_nop 0
	v_cvt_pk_u8_f32 v240, v230, 0, 0
	v_cvt_pk_u8_f32 v240, v232, 1, v240
	v_cvt_pk_u8_f32 v240, v234, 2, v240
	v_cvt_pk_u8_f32 v240, v236, 3, v240
	v_cvt_pk_u8_f32 v241, v231, 0, 0
	v_cvt_pk_u8_f32 v241, v233, 1, v241
	v_cvt_pk_u8_f32 v241, v235, 2, v241
	v_cvt_pk_u8_f32 v241, v237, 3, v241
	global_store_dwordx2 v[186:187], v[240:241], off offset:128
	v_fma_f32 v230, v106, v170, v10
	v_fma_f32 v231, v107, v170, v11
	v_fma_f32 v232, v110, v170, v14
	v_fma_f32 v233, v111, v170, v15
	v_fma_f32 v234, v112, v170, v16
	v_fma_f32 v235, v108, v170, v12
	v_fma_f32 v236, v113, v170, v17
	v_fma_f32 v237, v109, v170, v13
	v_exp_f32_e32 v230, v230
	v_exp_f32_e32 v231, v231
	v_exp_f32_e32 v232, v232
	v_exp_f32_e32 v233, v233
	v_exp_f32_e32 v234, v234
	v_exp_f32_e32 v235, v235
	v_exp_f32_e32 v236, v236
	v_exp_f32_e32 v237, v237
	s_nop 0
	v_fma_f32 v230, v230, s98, s98 clamp
	v_fma_f32 v231, v231, s98, s98 clamp
	v_fma_f32 v232, v232, s98, s98 clamp
	v_fma_f32 v233, v233, s98, s98 clamp
; __device__ __forceinline__ float sigmoidf_(float x) { return frcp(1.0f + fexp(-x)); }
;     __device__ __forceinline__ void operator()(const Acc& acc, const Unit& u, int wr, int wc, int fr, int fq) const {
;     ...
;             for (int m = 0; m < 4; ++m) { const int row = row0 + ai * HALF + m * 16; const float rs = rsv[ai][m]; unsigned char* rowp = GT + (size_t)row * NGT + colt;
; #pragma unroll
;                 for (int bj = 0; bj < 2; ++bj) { f32x4 v0 = acc[ai][bj][m][0] * rs + bv[bj][0], v1 = acc[ai][bj][m][1] * rs + bv[bj][1];
;                     unsigned q0[4], q1[4];
; #pragma unroll
;                     for (int e = 0; e < 4; ++e) { q0[e] = (unsigned)fmaxf(sigmoidf_(v0[e]) * 255.0f + 0.5f, 1.0f); q1[e] = (unsigned)fmaxf(sigmoidf_(v1[e]) * 255.0f + 0.5f, 1.0f); }
;                     u32x2 w; w.x = q0[0] | (q0[1] << 8) | (q0[2] << 16) | (q0[3] << 24); w.y = q1[0] | (q1[1] << 8) | (q1[2] << 16) | (q1[3] << 24);
;                     *(u32x2*)(rowp + bj * HALF) = w; } }
	v_fma_f32 v234, v234, s98, s98 clamp
	v_fma_f32 v235, v235, s98, s98 clamp
	v_fma_f32 v236, v236, s98, s98 clamp
	v_fma_f32 v237, v237, s98, s98 clamp
	v_rcp_f32_e32 v230, v230
	v_rcp_f32_e32 v231, v231
	v_rcp_f32_e32 v232, v232
	v_rcp_f32_e32 v233, v233
	v_rcp_f32_e32 v234, v234
	v_rcp_f32_e32 v235, v235
	v_rcp_f32_e32 v236, v236
	v_rcp_f32_e32 v237, v237
	s_nop 0
	v_cvt_pk_u8_f32 v242, v232, 0, 0
	v_cvt_pk_u8_f32 v242, v233, 1, v242
	v_cvt_pk_u8_f32 v242, v234, 2, v242
	v_cvt_pk_u8_f32 v242, v236, 3, v242
	v_cvt_pk_u8_f32 v243, v230, 0, 0
	v_cvt_pk_u8_f32 v243, v231, 1, v243
	v_cvt_pk_u8_f32 v243, v235, 2, v243
	v_cvt_pk_u8_f32 v243, v237, 3, v243
	v_mad_i64_i32 v[184:185], s[42:43], v18, s62, v[28:29]
	v_lshl_add_u64 v[184:185], v[184:185], 0, v[26:27]
	global_store_dwordx2 v[184:185], v[242:243], off
	v_fma_f32 v230, v98, v170, v2
	v_fma_f32 v231, v99, v170, v3
	v_fma_f32 v232, v102, v170, v6
	v_fma_f32 v233, v100, v170, v4
	v_fma_f32 v234, v103, v170, v7
	v_fma_f32 v235, v104, v170, v8
	v_fma_f32 v236, v105, v170, v9
	v_fma_f32 v237, v101, v170, v5
	v_exp_f32_e32 v230, v230
	v_exp_f32_e32 v231, v231
	v_exp_f32_e32 v232, v232
	v_exp_f32_e32 v233, v233
	v_exp_f32_e32 v234, v234
	v_exp_f32_e32 v235, v235
	v_exp_f32_e32 v236, v236
	v_exp_f32_e32 v237, v237
	s_nop 0
	v_fma_f32 v230, v230, s98, s98 clamp
	v_fma_f32 v231, v231, s98, s98 clamp
	v_fma_f32 v232, v232, s98, s98 clamp
	v_fma_f32 v233, v233, s98, s98 clamp
	v_fma_f32 v234, v234, s98, s98 clamp
	v_fma_f32 v235, v235, s98, s98 clamp
	v_fma_f32 v236, v236, s98, s98 clamp
	v_fma_f32 v237, v237, s98, s98 clamp
	v_rcp_f32_e32 v230, v230
	v_rcp_f32_e32 v231, v231
	v_rcp_f32_e32 v232, v232
	v_rcp_f32_e32 v233, v233
	v_rcp_f32_e32 v234, v234
	v_rcp_f32_e32 v235, v235
	v_rcp_f32_e32 v236, v236
	v_rcp_f32_e32 v237, v237
	s_nop 0
	v_cvt_pk_u8_f32 v244, v232, 0, 0
	v_cvt_pk_u8_f32 v244, v234, 1, v244
	v_cvt_pk_u8_f32 v244, v235, 2, v244
	v_cvt_pk_u8_f32 v244, v236, 3, v244
	v_cvt_pk_u8_f32 v245, v230, 0, 0
	v_cvt_pk_u8_f32 v245, v231, 1, v245
	v_cvt_pk_u8_f32 v245, v233, 2, v245
	v_cvt_pk_u8_f32 v245, v237, 3, v245
	global_store_dwordx2 v[184:185], v[244:245], off offset:128
	v_fma_f32 v230, v90, v33, v10
	v_fma_f32 v231, v91, v33, v11
	v_fma_f32 v232, v92, v33, v12
	v_fma_f32 v233, v94, v33, v14
	v_fma_f32 v234, v95, v33, v15
	v_fma_f32 v235, v96, v33, v16
	v_fma_f32 v236, v97, v33, v17
	v_fma_f32 v237, v93, v33, v13
	v_exp_f32_e32 v230, v230
	v_exp_f32_e32 v231, v231
	v_exp_f32_e32 v232, v232
	v_exp_f32_e32 v233, v233
	v_exp_f32_e32 v234, v234
	v_exp_f32_e32 v235, v235
	v_exp_f32_e32 v236, v236
	v_exp_f32_e32 v237, v237
	s_nop 0
	v_fma_f32 v230, v230, s98, s98 clamp
	v_fma_f32 v231, v231, s98, s98 clamp
	v_fma_f32 v232, v232, s98, s98 clamp
	v_fma_f32 v233, v233, s98, s98 clamp
	v_fma_f32 v234, v234, s98, s98 clamp
	v_fma_f32 v235, v235, s98, s98 clamp
	v_fma_f32 v236, v236, s98, s98 clamp
	v_fma_f32 v237, v237, s98, s98 clamp
	v_rcp_f32_e32 v230, v230
	v_rcp_f32_e32 v231, v231
	v_rcp_f32_e32 v232, v232
	v_rcp_f32_e32 v233, v233
	v_rcp_f32_e32 v234, v234
	v_rcp_f32_e32 v235, v235
	v_rcp_f32_e32 v236, v236
	v_rcp_f32_e32 v237, v237
	s_nop 0
	v_cvt_pk_u8_f32 v238, v233, 0, 0
	v_cvt_pk_u8_f32 v238, v234, 1, v238
	v_cvt_pk_u8_f32 v238, v235, 2, v238
	v_cvt_pk_u8_f32 v238, v236, 3, v238
	v_cvt_pk_u8_f32 v239, v230, 0, 0
	v_cvt_pk_u8_f32 v239, v231, 1, v239
	v_cvt_pk_u8_f32 v239, v232, 2, v239
	v_cvt_pk_u8_f32 v239, v237, 3, v239
	v_mad_i64_i32 v[184:185], s[42:43], v183, s62, v[28:29]
	v_lshl_add_u64 v[184:185], v[184:185], 0, v[26:27]
	global_store_dwordx2 v[184:185], v[238:239], off
	v_fma_f32 v230, v82, v33, v2
	v_fma_f32 v231, v83, v33, v3
	v_fma_f32 v232, v84, v33, v4
	v_fma_f32 v233, v86, v33, v6
	v_fma_f32 v234, v87, v33, v7
	v_fma_f32 v235, v88, v33, v8
	v_fma_f32 v236, v89, v33, v9
	v_fma_f32 v237, v85, v33, v5
	v_exp_f32_e32 v230, v230
	v_exp_f32_e32 v231, v231
	v_exp_f32_e32 v232, v232
	v_exp_f32_e32 v233, v233
	v_exp_f32_e32 v234, v234
	v_exp_f32_e32 v235, v235
	v_exp_f32_e32 v236, v236
	v_exp_f32_e32 v237, v237
	s_nop 0
	v_fma_f32 v230, v230, s98, s98 clamp
	v_fma_f32 v231, v231, s98, s98 clamp
	v_fma_f32 v232, v232, s98, s98 clamp
	v_fma_f32 v233, v233, s98, s98 clamp
	v_fma_f32 v234, v234, s98, s98 clamp
	v_fma_f32 v235, v235, s98, s98 clamp
	v_fma_f32 v236, v236, s98, s98 clamp
	v_fma_f32 v237, v237, s98, s98 clamp
	v_rcp_f32_e32 v230, v230
	v_rcp_f32_e32 v231, v231
	v_rcp_f32_e32 v232, v232
	v_rcp_f32_e32 v233, v233
	v_rcp_f32_e32 v234, v234
	v_rcp_f32_e32 v235, v235
	v_rcp_f32_e32 v236, v236
	v_rcp_f32_e32 v237, v237
	s_nop 0
	v_cvt_pk_u8_f32 v240, v233, 0, 0
	v_cvt_pk_u8_f32 v240, v234, 1, v240
	v_cvt_pk_u8_f32 v240, v235, 2, v240
	v_cvt_pk_u8_f32 v240, v236, 3, v240
	v_cvt_pk_u8_f32 v241, v230, 0, 0
	v_cvt_pk_u8_f32 v241, v231, 1, v241
	v_cvt_pk_u8_f32 v241, v232, 2, v241
	v_cvt_pk_u8_f32 v241, v237, 3, v241
	global_store_dwordx2 v[184:185], v[240:241], off offset:128
	v_fma_f32 v230, v78, v32, v14
	v_fma_f32 v231, v79, v32, v15
	v_fma_f32 v232, v74, v32, v10
	v_fma_f32 v233, v75, v32, v11
	v_fma_f32 v234, v80, v32, v16
	v_fma_f32 v235, v81, v32, v17
	v_fma_f32 v236, v76, v32, v12
	v_fma_f32 v237, v77, v32, v13
	v_exp_f32_e32 v230, v230
	v_exp_f32_e32 v231, v231
	v_exp_f32_e32 v232, v232
	v_exp_f32_e32 v233, v233
	v_exp_f32_e32 v234, v234
	v_exp_f32_e32 v235, v235
	v_exp_f32_e32 v236, v236
	v_exp_f32_e32 v237, v237
	s_nop 0
	v_fma_f32 v230, v230, s98, s98 clamp
	v_fma_f32 v231, v231, s98, s98 clamp
	v_fma_f32 v232, v232, s98, s98 clamp
	v_fma_f32 v233, v233, s98, s98 clamp
	v_fma_f32 v234, v234, s98, s98 clamp
	v_fma_f32 v235, v235, s98, s98 clamp
	v_fma_f32 v236, v236, s98, s98 clamp
; __device__ __forceinline__ float sigmoidf_(float x) { return frcp(1.0f + fexp(-x)); }
;     __device__ __forceinline__ void operator()(const Acc& acc, const Unit& u, int wr, int wc, int fr, int fq) const {
;     ...
;             for (int m = 0; m < 4; ++m) { const int row = row0 + ai * HALF + m * 16; const float rs = rsv[ai][m]; unsigned char* rowp = GT + (size_t)row * NGT + colt;
; #pragma unroll
;                 for (int bj = 0; bj < 2; ++bj) { f32x4 v0 = acc[ai][bj][m][0] * rs + bv[bj][0], v1 = acc[ai][bj][m][1] * rs + bv[bj][1];
;                     unsigned q0[4], q1[4];
; #pragma unroll
;                     for (int e = 0; e < 4; ++e) { q0[e] = (unsigned)fmaxf(sigmoidf_(v0[e]) * 255.0f + 0.5f, 1.0f); q1[e] = (unsigned)fmaxf(sigmoidf_(v1[e]) * 255.0f + 0.5f, 1.0f); }
;                     u32x2 w; w.x = q0[0] | (q0[1] << 8) | (q0[2] << 16) | (q0[3] << 24); w.y = q1[0] | (q1[1] << 8) | (q1[2] << 16) | (q1[3] << 24);
;                     *(u32x2*)(rowp + bj * HALF) = w; } }
	v_fma_f32 v237, v237, s98, s98 clamp
	v_rcp_f32_e32 v230, v230
	v_rcp_f32_e32 v231, v231
	v_rcp_f32_e32 v232, v232
	v_rcp_f32_e32 v233, v233
	v_rcp_f32_e32 v234, v234
	v_rcp_f32_e32 v235, v235
	v_rcp_f32_e32 v236, v236
	v_rcp_f32_e32 v237, v237
	s_nop 0
	v_cvt_pk_u8_f32 v242, v230, 0, 0
	v_cvt_pk_u8_f32 v242, v231, 1, v242
	v_cvt_pk_u8_f32 v242, v234, 2, v242
	v_cvt_pk_u8_f32 v242, v235, 3, v242
	v_cvt_pk_u8_f32 v243, v232, 0, 0
	v_cvt_pk_u8_f32 v243, v233, 1, v243
	v_cvt_pk_u8_f32 v243, v236, 2, v243
	v_cvt_pk_u8_f32 v243, v237, 3, v243
	v_mad_i64_i32 v[184:185], s[42:43], v182, s62, v[28:29]
	v_lshl_add_u64 v[184:185], v[184:185], 0, v[26:27]
	global_store_dwordx2 v[184:185], v[242:243], off
	v_fma_f32 v230, v70, v32, v6
	v_fma_f32 v231, v66, v32, v2
	v_fma_f32 v232, v71, v32, v7
	v_fma_f32 v233, v67, v32, v3
	v_fma_f32 v234, v72, v32, v8
	v_fma_f32 v235, v68, v32, v4
	v_fma_f32 v236, v73, v32, v9
	v_fma_f32 v237, v69, v32, v5
	v_exp_f32_e32 v230, v230
	v_exp_f32_e32 v231, v231
	v_exp_f32_e32 v232, v232
	v_exp_f32_e32 v233, v233
	v_exp_f32_e32 v234, v234
	v_exp_f32_e32 v235, v235
	v_exp_f32_e32 v236, v236
	v_exp_f32_e32 v237, v237
	s_nop 0
	v_fma_f32 v230, v230, s98, s98 clamp
	v_fma_f32 v231, v231, s98, s98 clamp
	v_fma_f32 v232, v232, s98, s98 clamp
	v_fma_f32 v233, v233, s98, s98 clamp
	v_fma_f32 v234, v234, s98, s98 clamp
	v_fma_f32 v235, v235, s98, s98 clamp
	v_fma_f32 v236, v236, s98, s98 clamp
	v_fma_f32 v237, v237, s98, s98 clamp
	v_rcp_f32_e32 v230, v230
	v_rcp_f32_e32 v231, v231
	v_rcp_f32_e32 v232, v232
	v_rcp_f32_e32 v233, v233
	v_rcp_f32_e32 v234, v234
	v_rcp_f32_e32 v235, v235
	v_rcp_f32_e32 v236, v236
	v_rcp_f32_e32 v237, v237
	s_nop 0
	v_cvt_pk_u8_f32 v244, v230, 0, 0
	v_cvt_pk_u8_f32 v244, v232, 1, v244
	v_cvt_pk_u8_f32 v244, v234, 2, v244
	v_cvt_pk_u8_f32 v244, v236, 3, v244
	v_cvt_pk_u8_f32 v245, v231, 0, 0
	v_cvt_pk_u8_f32 v245, v233, 1, v245
	v_cvt_pk_u8_f32 v245, v235, 2, v245
	v_cvt_pk_u8_f32 v245, v237, 3, v245
	global_store_dwordx2 v[184:185], v[244:245], off offset:128
	v_mad_i64_i32 v[32:33], s[42:43], v181, s62, v[28:29]
	v_fma_f32 v230, v58, v31, v10
	v_fma_f32 v231, v59, v31, v11
	v_fma_f32 v232, v63, v31, v15
	v_fma_f32 v233, v60, v31, v12
	v_fma_f32 v234, v62, v31, v14
	v_fma_f32 v235, v64, v31, v16
	v_fma_f32 v236, v65, v31, v17
	v_fma_f32 v237, v61, v31, v13
	v_exp_f32_e32 v230, v230
	v_exp_f32_e32 v231, v231
	v_exp_f32_e32 v232, v232
	v_exp_f32_e32 v233, v233
	v_exp_f32_e32 v234, v234
	v_exp_f32_e32 v235, v235
	v_exp_f32_e32 v236, v236
	v_exp_f32_e32 v237, v237
	s_nop 0
	v_fma_f32 v230, v230, s98, s98 clamp
	v_fma_f32 v231, v231, s98, s98 clamp
	v_fma_f32 v232, v232, s98, s98 clamp
	v_fma_f32 v233, v233, s98, s98 clamp
	v_fma_f32 v234, v234, s98, s98 clamp
	v_fma_f32 v235, v235, s98, s98 clamp
	v_fma_f32 v236, v236, s98, s98 clamp
	v_fma_f32 v237, v237, s98, s98 clamp
	v_rcp_f32_e32 v230, v230
	v_rcp_f32_e32 v231, v231
	v_rcp_f32_e32 v232, v232
	v_rcp_f32_e32 v233, v233
	v_rcp_f32_e32 v234, v234
	v_rcp_f32_e32 v235, v235
	v_rcp_f32_e32 v236, v236
	v_rcp_f32_e32 v237, v237
	s_nop 0
	v_cvt_pk_u8_f32 v238, v234, 0, 0
	v_cvt_pk_u8_f32 v238, v232, 1, v238
	v_cvt_pk_u8_f32 v238, v235, 2, v238
	v_cvt_pk_u8_f32 v238, v236, 3, v238
	v_cvt_pk_u8_f32 v239, v230, 0, 0
	v_cvt_pk_u8_f32 v239, v231, 1, v239
	v_cvt_pk_u8_f32 v239, v233, 2, v239
	v_cvt_pk_u8_f32 v239, v237, 3, v239
	v_mad_i64_i32 v[28:29], s[42:43], v180, s62, v[28:29]
	v_lshl_add_u64 v[32:33], v[32:33], 0, v[26:27]
	v_lshl_add_u64 v[26:27], v[28:29], 0, v[26:27]
	v_fma_f32 v230, v42, v30, v10
	v_fma_f32 v231, v47, v30, v15
	v_fma_f32 v232, v43, v30, v11
	v_fma_f32 v233, v48, v30, v16
	v_fma_f32 v234, v44, v30, v12
	v_fma_f32 v235, v46, v30, v14
	v_fma_f32 v236, v49, v30, v17
	v_fma_f32 v237, v45, v30, v13
	v_exp_f32_e32 v230, v230
; __device__ __forceinline__ float sigmoidf_(float x) { return frcp(1.0f + fexp(-x)); }
;     __device__ __forceinline__ void operator()(const Acc& acc, const Unit& u, int wr, int wc, int fr, int fq) const {
;     ...
;             for (int m = 0; m < 4; ++m) { const int row = row0 + ai * HALF + m * 16; const float rs = rsv[ai][m]; unsigned char* rowp = GT + (size_t)row * NGT + colt;
; #pragma unroll
;                 for (int bj = 0; bj < 2; ++bj) { f32x4 v0 = acc[ai][bj][m][0] * rs + bv[bj][0], v1 = acc[ai][bj][m][1] * rs + bv[bj][1];
;                     unsigned q0[4], q1[4];
; #pragma unroll
;                     for (int e = 0; e < 4; ++e) { q0[e] = (unsigned)fmaxf(sigmoidf_(v0[e]) * 255.0f + 0.5f, 1.0f); q1[e] = (unsigned)fmaxf(sigmoidf_(v1[e]) * 255.0f + 0.5f, 1.0f); }
;                     u32x2 w; w.x = q0[0] | (q0[1] << 8) | (q0[2] << 16) | (q0[3] << 24); w.y = q1[0] | (q1[1] << 8) | (q1[2] << 16) | (q1[3] << 24);
;                     *(u32x2*)(rowp + bj * HALF) = w; } }
	v_exp_f32_e32 v231, v231
	v_exp_f32_e32 v232, v232
	v_exp_f32_e32 v233, v233
	v_exp_f32_e32 v234, v234
	v_exp_f32_e32 v235, v235
	v_exp_f32_e32 v236, v236
	v_exp_f32_e32 v237, v237
	s_nop 0
	v_fma_f32 v230, v230, s98, s98 clamp
	v_fma_f32 v231, v231, s98, s98 clamp
	v_fma_f32 v232, v232, s98, s98 clamp
	v_fma_f32 v233, v233, s98, s98 clamp
	v_fma_f32 v234, v234, s98, s98 clamp
	v_fma_f32 v235, v235, s98, s98 clamp
	v_fma_f32 v236, v236, s98, s98 clamp
	v_fma_f32 v237, v237, s98, s98 clamp
	v_rcp_f32_e32 v230, v230
	v_rcp_f32_e32 v231, v231
	v_rcp_f32_e32 v232, v232
	v_rcp_f32_e32 v233, v233
	v_rcp_f32_e32 v234, v234
	v_rcp_f32_e32 v235, v235
	v_rcp_f32_e32 v236, v236
	v_rcp_f32_e32 v237, v237
	s_nop 0
	v_cvt_pk_u8_f32 v240, v235, 0, 0
	v_cvt_pk_u8_f32 v240, v231, 1, v240
	v_cvt_pk_u8_f32 v240, v233, 2, v240
	v_cvt_pk_u8_f32 v240, v236, 3, v240
	v_cvt_pk_u8_f32 v241, v230, 0, 0
	v_cvt_pk_u8_f32 v241, v232, 1, v241
	v_cvt_pk_u8_f32 v241, v234, 2, v241
	v_cvt_pk_u8_f32 v241, v237, 3, v241
	global_store_dwordx2 v[32:33], v[238:239], off
	global_store_dwordx2 v[26:27], v[240:241], off
	v_fma_f32 v230, v50, v31, v2
	v_fma_f32 v231, v55, v31, v7
	v_fma_f32 v232, v51, v31, v3
	v_fma_f32 v233, v52, v31, v4
	v_fma_f32 v234, v54, v31, v6
	v_fma_f32 v235, v56, v31, v8
	v_fma_f32 v236, v57, v31, v9
	v_fma_f32 v237, v53, v31, v5
	v_exp_f32_e32 v230, v230
	v_exp_f32_e32 v231, v231
	v_exp_f32_e32 v232, v232
	v_exp_f32_e32 v233, v233
	v_exp_f32_e32 v234, v234
	v_exp_f32_e32 v235, v235
	v_exp_f32_e32 v236, v236
	v_exp_f32_e32 v237, v237
	s_nop 0
	v_fma_f32 v230, v230, s98, s98 clamp
	v_fma_f32 v231, v231, s98, s98 clamp
	v_fma_f32 v232, v232, s98, s98 clamp
	v_fma_f32 v233, v233, s98, s98 clamp
	v_fma_f32 v234, v234, s98, s98 clamp
	v_fma_f32 v235, v235, s98, s98 clamp
	v_fma_f32 v236, v236, s98, s98 clamp
	v_fma_f32 v237, v237, s98, s98 clamp
	v_rcp_f32_e32 v230, v230
	v_rcp_f32_e32 v231, v231
	v_rcp_f32_e32 v232, v232
	v_rcp_f32_e32 v233, v233
	v_rcp_f32_e32 v234, v234
	v_rcp_f32_e32 v235, v235
	v_rcp_f32_e32 v236, v236
	v_rcp_f32_e32 v237, v237
	s_nop 0
	v_cvt_pk_u8_f32 v242, v234, 0, 0
	v_cvt_pk_u8_f32 v242, v231, 1, v242
	v_cvt_pk_u8_f32 v242, v235, 2, v242
	v_cvt_pk_u8_f32 v242, v236, 3, v242
	v_cvt_pk_u8_f32 v243, v230, 0, 0
	v_cvt_pk_u8_f32 v243, v232, 1, v243
	v_cvt_pk_u8_f32 v243, v233, 2, v243
	v_cvt_pk_u8_f32 v243, v237, 3, v243
	v_fma_f32 v230, v34, v30, v2
	v_fma_f32 v231, v39, v30, v7
	v_fma_f32 v232, v35, v30, v3
	v_fma_f32 v233, v40, v30, v8
	v_fma_f32 v234, v36, v30, v4
	v_fma_f32 v235, v38, v30, v6
	v_fma_f32 v236, v41, v30, v9
	v_fma_f32 v237, v37, v30, v5
	v_exp_f32_e32 v230, v230
	v_exp_f32_e32 v231, v231
	v_exp_f32_e32 v232, v232
	v_exp_f32_e32 v233, v233
	v_exp_f32_e32 v234, v234
	v_exp_f32_e32 v235, v235
	v_exp_f32_e32 v236, v236
	v_exp_f32_e32 v237, v237
	s_nop 0
	v_fma_f32 v230, v230, s98, s98 clamp
	v_fma_f32 v231, v231, s98, s98 clamp
	v_fma_f32 v232, v232, s98, s98 clamp
	v_fma_f32 v233, v233, s98, s98 clamp
	v_fma_f32 v234, v234, s98, s98 clamp
	v_fma_f32 v235, v235, s98, s98 clamp
	v_fma_f32 v236, v236, s98, s98 clamp
	v_fma_f32 v237, v237, s98, s98 clamp
	v_rcp_f32_e32 v230, v230
	v_rcp_f32_e32 v231, v231
	v_rcp_f32_e32 v232, v232
	v_rcp_f32_e32 v233, v233
	v_rcp_f32_e32 v234, v234
	v_rcp_f32_e32 v235, v235
	v_rcp_f32_e32 v236, v236
	v_rcp_f32_e32 v237, v237
	s_nop 0
	v_cvt_pk_u8_f32 v244, v235, 0, 0
	v_cvt_pk_u8_f32 v244, v231, 1, v244
	v_cvt_pk_u8_f32 v244, v233, 2, v244
	v_cvt_pk_u8_f32 v244, v236, 3, v244
	v_cvt_pk_u8_f32 v245, v230, 0, 0
	v_cvt_pk_u8_f32 v245, v232, 1, v245
	v_cvt_pk_u8_f32 v245, v234, 2, v245
	v_cvt_pk_u8_f32 v245, v237, 3, v245
	global_store_dwordx2 v[32:33], v[242:243], off offset:128
	global_store_dwordx2 v[26:27], v[244:245], off offset:128
	s_cbranch_execz .LBB0_574
